# AP2 + accumulator chains adjacent also in the rotating-accumulator MFMA runs of the sliver K-loops (dependency-checked reorder)
# baseline (speedup 1.0000x reference)
; #define PG8_STAGE(bufoff, gbase, voff) do { _Pragma("unroll") for (int _i = 0; _i < 2; ++_i) \
;         __builtin_amdgcn_global_load_lds((const unsigned*)((const char*)(gbase) + (size_t)_i * qstep + (voff)[0]), (PG8_LAS unsigned*)(lds + (bufoff) + ldsw + _i * 8192), 16, 0, 0); } while (0)
; #define PG8_LDA(dst, b, h) do { _Pragma("unroll") for (int m = 0; m < 4; ++m) _Pragma("unroll") for (int k = 0; k < 2; ++k) dst[m][k] = *(const PG8_LAS bf16x8*)(lds + PG8_SA(b, h) + aoff + m * 2048 + k * 1024); } while (0)
; #define PG8_LDB(dst, b, h) do { _Pragma("unroll") for (int n = 0; n < 2; ++n) _Pragma("unroll") for (int k = 0; k < 2; ++k) dst[n][k] = *(const PG8_LAS bf16x8*)(lds + PG8_SB(b, h) + boff + n * 2048 + k * 1024); } while (0)
; #define PG8_MMA(ai, bj, At, Bt) do { __builtin_amdgcn_s_setprio(1); _Pragma("unroll") for (int m = 0; m < 4; ++m) _Pragma("unroll") for (int n = 0; n < 2; ++n) _Pragma("unroll") for (int k = 0; k < 2; ++k) \
;         acc[ai][bj][m][n] = __builtin_amdgcn_mfma_f32_16x16x32_bf16(Bt[n][k], At[m][k], acc[ai][bj][m][n], 0, 0, 0); __builtin_amdgcn_s_setprio(0); } while (0)
; #define PG8_WAIT_V89() do { if constexpr (SLIVER) PG8_WAIT_V(9); else PG8_WAIT_V(8); } while (0)
; #define PG8_STAGE_S(b, gbase) do { if constexpr (SLIVER) __builtin_amdgcn_global_load_lds((const unsigned*)((const char*)(gbase) + voffS), (PG8_LAS unsigned*)(lds + STAGE_BYTES + (b) * 2048 + wid * 256), 4, 0, 0); } while (0)
; #define PG8_WAIT_L(n) asm volatile("s_waitcnt lgkmcnt(" #n ")" ::: "memory")
; #define PG8_BAR __builtin_amdgcn_s_barrier()
; #define PG8_SCHED __builtin_amdgcn_sched_barrier(0)
; template <class Epi, class Sched, bool ALIGN_EPI = false, bool SP2 = false, bool SLIVER = false>
; __device__ __forceinline__ void gemm_phase(PG8_LAS unsigned char* lds, const Gemm g, const Sched& S, const Epi& E) {
;     ...
;             PG8_LDB(B0, 1, 0); PG8_LDB(B1, 1, 1); PG8_SCHED; PG8_LDA(At, 1, 0); PG8_STAGE(PG8_SA(0, 1), a2 + hstep, voffA); PG8_STAGE_S(0, s2);
;             PG8_WAIT_V89(); PG8_WAIT_L(0); PG8_BAR; PG8_MMA(0, 0, At, B0); PG8_MMA(0, 1, At, B1); PG8_BAR; PG8_SCHED;
.LBB0_502:
	s_barrier
	s_setprio 0
	s_add_u32 s68, s62, s80
	s_addc_u32 s69, s63, s81
	s_add_u32 s76, s68, 0x100
	s_addc_u32 s77, s69, 0
	s_and_b64 s[68:69], s[86:87], exec
	s_cselect_b32 s69, s85, s77
	s_cselect_b32 s68, s84, s76
	s_add_i32 s76, 0, 0x18000
	v_add_u32_e32 v82, s76, v239
	s_add_i32 s77, 0, 0x1c000
	ds_read_b128 v[146:149], v82
	ds_read_b128 v[150:153], v82 offset:1024
	ds_read_b128 v[154:157], v82 offset:2048
	ds_read_b128 v[158:161], v82 offset:3072
	v_add_u32_e32 v82, s77, v239
	ds_read_b128 v[166:169], v82
	ds_read_b128 v[170:173], v82 offset:1024
	ds_read_b128 v[174:177], v82 offset:2048
	ds_read_b128 v[162:165], v82 offset:3072
	s_mov_b32 m0, s91
	v_lshl_add_u64 v[208:209], v[194:195], 0, s[24:25]
	ds_read_b128 v[82:85], v242 offset:32768
	ds_read_b128 v[94:97], v242 offset:33792
	ds_read_b128 v[180:183], v242 offset:34816
	ds_read_b128 v[184:187], v242 offset:35840
	ds_read_b128 v[196:199], v242 offset:36864
	ds_read_b128 v[200:203], v242 offset:37888
	ds_read_b128 v[220:223], v242 offset:38912
	ds_read_b128 v[224:227], v242 offset:39936
	global_load_lds_dwordx4 v[208:209], off
	v_lshl_add_u64 v[208:209], v[194:195], 0, s[14:15]
	s_mov_b32 m0, s92
	s_nop 0
	global_load_lds_dwordx4 v[208:209], off
	v_lshl_add_u64 v[208:209], s[68:69], 0, v[214:215]
	s_mov_b32 m0, s93
	s_nop 0
	global_load_lds_dword v[208:209], off
	s_waitcnt vmcnt(9)
	s_waitcnt lgkmcnt(0)
	s_setprio 1
	s_barrier
	v_mfma_f32_16x16x32_bf16 v[134:137], v[146:149], v[82:85], v[134:137]
	v_mfma_f32_16x16x32_bf16 v[134:137], v[150:153], v[94:97], v[134:137]
	v_mfma_f32_16x16x32_bf16 v[130:133], v[154:157], v[82:85], v[130:133]
	v_mfma_f32_16x16x32_bf16 v[130:133], v[158:161], v[94:97], v[130:133]
	v_mfma_f32_16x16x32_bf16 v[126:129], v[146:149], v[180:183], v[126:129]
	v_mfma_f32_16x16x32_bf16 v[126:129], v[150:153], v[184:187], v[126:129]
	v_mfma_f32_16x16x32_bf16 v[122:125], v[154:157], v[180:183], v[122:125]
	v_mfma_f32_16x16x32_bf16 v[122:125], v[158:161], v[184:187], v[122:125]
	v_mfma_f32_16x16x32_bf16 v[118:121], v[146:149], v[196:199], v[118:121]
	v_mfma_f32_16x16x32_bf16 v[118:121], v[150:153], v[200:203], v[118:121]
	v_mfma_f32_16x16x32_bf16 v[114:117], v[154:157], v[196:199], v[114:117]
	v_mfma_f32_16x16x32_bf16 v[114:117], v[158:161], v[200:203], v[114:117]
	v_mfma_f32_16x16x32_bf16 v[110:113], v[146:149], v[220:223], v[110:113]
	v_mfma_f32_16x16x32_bf16 v[110:113], v[150:153], v[224:227], v[110:113]
	v_mfma_f32_16x16x32_bf16 v[106:109], v[154:157], v[220:223], v[106:109]
	v_mfma_f32_16x16x32_bf16 v[106:109], v[158:161], v[224:227], v[106:109]
	s_setprio 0
	s_setprio 1
	v_mfma_f32_16x16x32_bf16 v[102:105], v[166:169], v[82:85], v[102:105]
	v_mfma_f32_16x16x32_bf16 v[102:105], v[170:173], v[94:97], v[102:105]
	v_mfma_f32_16x16x32_bf16 v[82:85], v[174:177], v[82:85], v[98:101]
	v_mfma_f32_16x16x32_bf16 v[98:101], v[162:165], v[94:97], v[82:85]
	v_mfma_f32_16x16x32_bf16 v[82:85], v[166:169], v[180:183], v[90:93]
	v_mfma_f32_16x16x32_bf16 v[90:93], v[170:173], v[184:187], v[82:85]
	v_mfma_f32_16x16x32_bf16 v[82:85], v[174:177], v[180:183], v[86:89]
	v_mfma_f32_16x16x32_bf16 v[86:89], v[162:165], v[184:187], v[82:85]
	v_mfma_f32_16x16x32_bf16 v[78:81], v[166:169], v[196:199], v[78:81]
	v_mfma_f32_16x16x32_bf16 v[78:81], v[170:173], v[200:203], v[78:81]
	v_mfma_f32_16x16x32_bf16 v[74:77], v[174:177], v[196:199], v[74:77]
	v_mfma_f32_16x16x32_bf16 v[74:77], v[162:165], v[200:203], v[74:77]
	v_mfma_f32_16x16x32_bf16 v[70:73], v[166:169], v[220:223], v[70:73]
	v_mfma_f32_16x16x32_bf16 v[70:73], v[170:173], v[224:227], v[70:73]
	v_mfma_f32_16x16x32_bf16 v[66:69], v[174:177], v[220:223], v[66:69]
	v_mfma_f32_16x16x32_bf16 v[66:69], v[162:165], v[224:227], v[66:69]
	s_barrier
; #define PG8_SB(B) __builtin_amdgcn_rcpf(1.f + expneg(B))
; #define PG8_SB(B) __builtin_amdgcn_rcpf(1.f + expneg(B))
; #define PG8_STAGE(bufoff, gbase, voff) do { _Pragma("unroll") for (int _i = 0; _i < 2; ++_i) \
;         __builtin_amdgcn_global_load_lds((const unsigned*)((const char*)(gbase) + (size_t)_i * qstep + (voff)[0]), (PG8_LAS unsigned*)(lds + (bufoff) + ldsw + _i * 8192), 16, 0, 0); } while (0)
; #define PG8_LDA(dst, b, h) do { _Pragma("unroll") for (int m = 0; m < 4; ++m) _Pragma("unroll") for (int k = 0; k < 2; ++k) dst[m][k] = *(const PG8_LAS bf16x8*)(lds + PG8_SA(b, h) + aoff + m * 2048 + k * 1024); } while (0)
; #define PG8_MMA(ai, bj, At, Bt) do { __builtin_amdgcn_s_setprio(1); _Pragma("unroll") for (int m = 0; m < 4; ++m) _Pragma("unroll") for (int n = 0; n < 2; ++n) _Pragma("unroll") for (int k = 0; k < 2; ++k) \
;         acc[ai][bj][m][n] = __builtin_amdgcn_mfma_f32_16x16x32_bf16(Bt[n][k], At[m][k], acc[ai][bj][m][n], 0, 0, 0); __builtin_amdgcn_s_setprio(0); } while (0)
; #define PG8_WAIT_V89() do { if constexpr (SLIVER) PG8_WAIT_V(9); else PG8_WAIT_V(8); } while (0)
; #define PG8_LDS_S(b) do { if constexpr (SLIVER) { Sf[0] = *(const PG8_LAS bf16x8*)(lds + STAGE_BYTES + (b) * 2048 + soff0); Sf[1] = *(const PG8_LAS bf16x8*)(lds + STAGE_BYTES + (b) * 2048 + (soff0 ^ 64)); } } while (0)
; #define PG8_WAIT_L(n) asm volatile("s_waitcnt lgkmcnt(" #n ")" ::: "memory")
; #define PG8_BAR __builtin_amdgcn_s_barrier()
; #define PG8_SCHED __builtin_amdgcn_sched_barrier(0)
; template <class Epi, class Sched, bool ALIGN_EPI = false, bool SP2 = false, bool SLIVER = false>
; __device__ __forceinline__ void gemm_phase(PG8_LAS unsigned char* lds, const Gemm g, const Sched& S, const Epi& E) {
;     ...
;             PG8_LDA(At, 1, 1); PG8_LDS_S(1); PG8_STAGE(PG8_SB(1, 0), b3, voffB); PG8_STAGE(PG8_SB(1, 1), b3 + hstep, voffB); PG8_STAGE(PG8_SA(1, 0), a3, voffA);
;             PG8_WAIT_V89(); PG8_WAIT_L(0); PG8_BAR; PG8_MMA(1, 0, At, B0); PG8_MMA(1, 1, At, B1); PG8_MMA_S(); PG8_BAR; PG8_SCHED;
	s_setprio 0
	s_add_i32 s68, 0, 0x20800
	v_add_u32_e32 v178, s68, v240
	v_add_u32_e32 v184, s68, v241
	s_add_i32 s68, s76, s95
	v_lshl_add_u64 v[208:209], v[192:193], 0, s[26:27]
	s_mov_b32 m0, s68
	ds_read_b128 v[82:85], v242 offset:49152
	ds_read_b128 v[94:97], v242 offset:50176
	ds_read_b128 v[196:199], v242 offset:51200
	ds_read_b128 v[200:203], v242 offset:52224
	ds_read_b128 v[220:223], v242 offset:53248
	ds_read_b128 v[224:227], v242 offset:54272
	ds_read_b128 v[228:231], v242 offset:55296
	ds_read_b128 v[232:235], v242 offset:56320
	ds_read_b128 v[180:183], v178
	ds_read_b128 v[184:187], v184
	global_load_lds_dwordx4 v[208:209], off
	v_lshl_add_u64 v[208:209], v[192:193], 0, s[72:73]
	s_add_i32 m0, s68, 0x2000
	s_add_i32 s68, s77, s95
	global_load_lds_dwordx4 v[208:209], off
	v_lshl_add_u64 v[208:209], v[192:193], 0, s[34:35]
	s_mov_b32 m0, s68
	s_mov_b64 s[76:77], 0x120080
	global_load_lds_dwordx4 v[208:209], off
	v_lshl_add_u64 v[192:193], v[192:193], 0, s[76:77]
	s_add_i32 m0, s68, 0x2000
	s_nop 0
	global_load_lds_dwordx4 v[192:193], off
	v_lshl_add_u64 v[192:193], v[194:195], 0, s[26:27]
	s_mov_b32 m0, s97
	s_nop 0
	global_load_lds_dwordx4 v[192:193], off
	v_lshl_add_u64 v[192:193], v[194:195], 0, s[72:73]
	s_mov_b32 m0, s18
	s_nop 0
	global_load_lds_dwordx4 v[192:193], off
	s_waitcnt vmcnt(9)
	s_waitcnt lgkmcnt(0)
	s_setprio 1
	s_barrier
	v_mfma_f32_16x16x32_bf16 v[62:65], v[146:149], v[82:85], v[62:65]
	v_mfma_f32_16x16x32_bf16 v[62:65], v[150:153], v[94:97], v[62:65]
	v_mfma_f32_16x16x32_bf16 v[58:61], v[154:157], v[82:85], v[58:61]
	v_mfma_f32_16x16x32_bf16 v[58:61], v[158:161], v[94:97], v[58:61]
	v_mfma_f32_16x16x32_bf16 v[54:57], v[146:149], v[196:199], v[54:57]
	v_mfma_f32_16x16x32_bf16 v[54:57], v[150:153], v[200:203], v[54:57]
	v_mfma_f32_16x16x32_bf16 v[50:53], v[154:157], v[196:199], v[50:53]
	v_mfma_f32_16x16x32_bf16 v[50:53], v[158:161], v[200:203], v[50:53]
	v_mfma_f32_16x16x32_bf16 v[46:49], v[146:149], v[220:223], v[46:49]
	v_mfma_f32_16x16x32_bf16 v[46:49], v[150:153], v[224:227], v[46:49]
	v_mfma_f32_16x16x32_bf16 v[42:45], v[154:157], v[220:223], v[42:45]
	v_mfma_f32_16x16x32_bf16 v[42:45], v[158:161], v[224:227], v[42:45]
	v_mfma_f32_16x16x32_bf16 v[38:41], v[146:149], v[228:231], v[38:41]
	v_mfma_f32_16x16x32_bf16 v[38:41], v[150:153], v[232:235], v[38:41]
	v_mfma_f32_16x16x32_bf16 v[34:37], v[154:157], v[228:231], v[34:37]
	v_mfma_f32_16x16x32_bf16 v[34:37], v[158:161], v[232:235], v[34:37]
	s_setprio 0
	s_setprio 1
	v_mfma_f32_16x16x32_bf16 v[30:33], v[166:169], v[82:85], v[30:33]
	v_mfma_f32_16x16x32_bf16 v[30:33], v[170:173], v[94:97], v[30:33]
	v_mfma_f32_16x16x32_bf16 v[26:29], v[174:177], v[82:85], v[26:29]
	v_mfma_f32_16x16x32_bf16 v[26:29], v[162:165], v[94:97], v[26:29]
	v_mfma_f32_16x16x32_bf16 v[22:25], v[166:169], v[196:199], v[22:25]
	v_mfma_f32_16x16x32_bf16 v[22:25], v[170:173], v[200:203], v[22:25]
	v_mfma_f32_16x16x32_bf16 v[18:21], v[174:177], v[196:199], v[18:21]
	v_mfma_f32_16x16x32_bf16 v[18:21], v[162:165], v[200:203], v[18:21]
	v_mfma_f32_16x16x32_bf16 v[14:17], v[166:169], v[220:223], v[14:17]
	v_mfma_f32_16x16x32_bf16 v[14:17], v[170:173], v[224:227], v[14:17]
	v_mfma_f32_16x16x32_bf16 v[10:13], v[174:177], v[220:223], v[10:13]
	v_mfma_f32_16x16x32_bf16 v[10:13], v[162:165], v[224:227], v[10:13]
	v_mfma_f32_16x16x32_bf16 v[6:9], v[166:169], v[228:231], v[6:9]
	v_mfma_f32_16x16x32_bf16 v[6:9], v[170:173], v[232:235], v[6:9]
	v_mfma_f32_16x16x32_bf16 v[2:5], v[174:177], v[228:231], v[2:5]
	v_mfma_f32_16x16x32_bf16 v[2:5], v[162:165], v[232:235], v[2:5]
	s_setprio 0
	s_setprio 1
	s_and_b64 vcc, exec, s[52:53]
	s_cbranch_vccz .Lslv_c0
	v_mfma_f32_16x16x32_bf16 v[82:85], v[166:169], v[180:183], v[138:141]
	v_mfma_f32_16x16x32_bf16 v[94:97], v[174:177], v[180:183], v[142:145]
	v_mfma_f32_16x16x32_bf16 v[82:85], v[170:173], v[184:187], v[82:85]
	v_mfma_f32_16x16x32_bf16 v[94:97], v[162:165], v[184:187], v[94:97]
	s_branch .LBB0_497

; #define PG8_STAGE(bufoff, gbase, voff) do { _Pragma("unroll") for (int _i = 0; _i < 2; ++_i) \
;         __builtin_amdgcn_global_load_lds((const unsigned*)((const char*)(gbase) + (size_t)_i * qstep + (voff)[0]), (PG8_LAS unsigned*)(lds + (bufoff) + ldsw + _i * 8192), 16, 0, 0); } while (0)
; #define PG8_LDA(dst, b, h) do { _Pragma("unroll") for (int m = 0; m < 4; ++m) _Pragma("unroll") for (int k = 0; k < 2; ++k) dst[m][k] = *(const PG8_LAS bf16x8*)(lds + PG8_SA(b, h) + aoff + m * 2048 + k * 1024); } while (0)
; #define PG8_LDB(dst, b, h) do { _Pragma("unroll") for (int n = 0; n < 2; ++n) _Pragma("unroll") for (int k = 0; k < 2; ++k) dst[n][k] = *(const PG8_LAS bf16x8*)(lds + PG8_SB(b, h) + boff + n * 2048 + k * 1024); } while (0)
; #define PG8_MMA(ai, bj, At, Bt) do { __builtin_amdgcn_s_setprio(1); _Pragma("unroll") for (int m = 0; m < 4; ++m) _Pragma("unroll") for (int n = 0; n < 2; ++n) _Pragma("unroll") for (int k = 0; k < 2; ++k) \
;         acc[ai][bj][m][n] = __builtin_amdgcn_mfma_f32_16x16x32_bf16(Bt[n][k], At[m][k], acc[ai][bj][m][n], 0, 0, 0); __builtin_amdgcn_s_setprio(0); } while (0)
; #define PG8_WAIT_V89() do { if constexpr (SLIVER) PG8_WAIT_V(9); else PG8_WAIT_V(8); } while (0)
; #define PG8_STAGE_S(b, gbase) do { if constexpr (SLIVER) __builtin_amdgcn_global_load_lds((const unsigned*)((const char*)(gbase) + voffS), (PG8_LAS unsigned*)(lds + STAGE_BYTES + (b) * 2048 + wid * 256), 4, 0, 0); } while (0)
; #define PG8_WAIT_L(n) asm volatile("s_waitcnt lgkmcnt(" #n ")" ::: "memory")
; #define PG8_BAR __builtin_amdgcn_s_barrier()
; #define PG8_SCHED __builtin_amdgcn_sched_barrier(0)
; template <class Epi, class Sched, bool ALIGN_EPI = false, bool SP2 = false, bool SLIVER = false>
; __device__ __forceinline__ void gemm_phase(PG8_LAS unsigned char* lds, const Gemm g, const Sched& S, const Epi& E) {
;     ...
;             PG8_LDB(B0, 1, 0); PG8_LDB(B1, 1, 1); PG8_SCHED; PG8_LDA(At, 1, 0); PG8_STAGE(PG8_SA(0, 1), a2 + hstep, voffA); PG8_STAGE_S(0, s2);
;             PG8_WAIT_V89(); PG8_WAIT_L(0); PG8_BAR; PG8_MMA(0, 0, At, B0); PG8_MMA(0, 1, At, B1); PG8_BAR; PG8_SCHED;
.LBB0_602:
	s_barrier
	s_setprio 0
	s_add_u32 s77, s94, s62
	s_addc_u32 s78, s95, s63
	s_add_u32 s77, s77, 0x100
	s_addc_u32 s83, s78, 0
	s_and_b64 s[78:79], s[80:81], exec
	s_cselect_b32 s79, s66, s83
	s_cselect_b32 s78, s67, s77
	s_add_i32 s77, 0, 0x18000
	v_add_u32_e32 v2, s77, v212
	s_add_i32 s80, 0, 0x1c000
	ds_read_b128 v[146:149], v2
	ds_read_b128 v[150:153], v2 offset:1024
	ds_read_b128 v[154:157], v2 offset:2048
	ds_read_b128 v[158:161], v2 offset:3072
	v_add_u32_e32 v2, s80, v212
	ds_read_b128 v[166:169], v2
	ds_read_b128 v[170:173], v2 offset:1024
	ds_read_b128 v[174:177], v2 offset:2048
	ds_read_b128 v[162:165], v2 offset:3072
	s_mov_b32 m0, s49
	v_lshl_add_u64 v[208:209], v[210:211], 0, s[22:23]
	ds_read_b128 v[2:5], v215 offset:32768
	ds_read_b128 v[6:9], v215 offset:33792
	ds_read_b128 v[180:183], v215 offset:34816
	ds_read_b128 v[184:187], v215 offset:35840
	ds_read_b128 v[216:219], v215 offset:36864
	ds_read_b128 v[220:223], v215 offset:37888
	ds_read_b128 v[224:227], v215 offset:38912
	ds_read_b128 v[228:231], v215 offset:39936
	global_load_lds_dwordx4 v[208:209], off
	v_lshl_add_u64 v[208:209], v[210:211], 0, s[24:25]
	s_mov_b32 m0, s50
	s_nop 0
	global_load_lds_dwordx4 v[208:209], off
	v_lshl_add_u64 v[208:209], s[78:79], 0, v[192:193]
	s_mov_b32 m0, s51
	s_nop 0
	global_load_lds_dword v[208:209], off
	s_waitcnt vmcnt(9)
	s_waitcnt lgkmcnt(0)
	s_setprio 1
	s_barrier
	v_mfma_f32_16x16x32_bf16 v[134:137], v[146:149], v[2:5], v[134:137]
	v_mfma_f32_16x16x32_bf16 v[134:137], v[150:153], v[6:9], v[134:137]
	v_mfma_f32_16x16x32_bf16 v[130:133], v[154:157], v[2:5], v[130:133]
	v_mfma_f32_16x16x32_bf16 v[130:133], v[158:161], v[6:9], v[130:133]
	v_mfma_f32_16x16x32_bf16 v[118:121], v[146:149], v[180:183], v[118:121]
	v_mfma_f32_16x16x32_bf16 v[118:121], v[150:153], v[184:187], v[118:121]
	v_mfma_f32_16x16x32_bf16 v[114:117], v[154:157], v[180:183], v[114:117]
	v_mfma_f32_16x16x32_bf16 v[114:117], v[158:161], v[184:187], v[114:117]
	v_mfma_f32_16x16x32_bf16 v[102:105], v[146:149], v[216:219], v[102:105]
	v_mfma_f32_16x16x32_bf16 v[102:105], v[150:153], v[220:223], v[102:105]
	v_mfma_f32_16x16x32_bf16 v[98:101], v[154:157], v[216:219], v[98:101]
	v_mfma_f32_16x16x32_bf16 v[98:101], v[158:161], v[220:223], v[98:101]
	v_mfma_f32_16x16x32_bf16 v[86:89], v[146:149], v[224:227], v[86:89]
	v_mfma_f32_16x16x32_bf16 v[86:89], v[150:153], v[228:231], v[86:89]
	v_mfma_f32_16x16x32_bf16 v[82:85], v[154:157], v[224:227], v[82:85]
	v_mfma_f32_16x16x32_bf16 v[82:85], v[158:161], v[228:231], v[82:85]
	s_setprio 0
	s_setprio 1
	v_mfma_f32_16x16x32_bf16 v[126:129], v[166:169], v[2:5], v[126:129]
	v_mfma_f32_16x16x32_bf16 v[126:129], v[170:173], v[6:9], v[126:129]
	v_mfma_f32_16x16x32_bf16 v[2:5], v[174:177], v[2:5], v[122:125]
	v_mfma_f32_16x16x32_bf16 v[122:125], v[162:165], v[6:9], v[2:5]
	v_mfma_f32_16x16x32_bf16 v[2:5], v[166:169], v[180:183], v[110:113]
	v_mfma_f32_16x16x32_bf16 v[110:113], v[170:173], v[184:187], v[2:5]
	v_mfma_f32_16x16x32_bf16 v[2:5], v[174:177], v[180:183], v[106:109]
	v_mfma_f32_16x16x32_bf16 v[106:109], v[162:165], v[184:187], v[2:5]
	v_mfma_f32_16x16x32_bf16 v[2:5], v[166:169], v[216:219], v[94:97]
	v_mfma_f32_16x16x32_bf16 v[94:97], v[170:173], v[220:223], v[2:5]
	v_mfma_f32_16x16x32_bf16 v[2:5], v[174:177], v[216:219], v[90:93]
	v_mfma_f32_16x16x32_bf16 v[90:93], v[162:165], v[220:223], v[2:5]
	v_mfma_f32_16x16x32_bf16 v[2:5], v[166:169], v[224:227], v[78:81]
	v_mfma_f32_16x16x32_bf16 v[78:81], v[170:173], v[228:231], v[2:5]
	v_mfma_f32_16x16x32_bf16 v[2:5], v[174:177], v[224:227], v[74:77]
	v_mfma_f32_16x16x32_bf16 v[74:77], v[162:165], v[228:231], v[2:5]
	s_barrier
; #define PG8_SB(B) __builtin_amdgcn_rcpf(1.f + expneg(B))
; #define PG8_SB(B) __builtin_amdgcn_rcpf(1.f + expneg(B))
; #define PG8_STAGE(bufoff, gbase, voff) do { _Pragma("unroll") for (int _i = 0; _i < 2; ++_i) \
;         __builtin_amdgcn_global_load_lds((const unsigned*)((const char*)(gbase) + (size_t)_i * qstep + (voff)[0]), (PG8_LAS unsigned*)(lds + (bufoff) + ldsw + _i * 8192), 16, 0, 0); } while (0)
; #define PG8_LDA(dst, b, h) do { _Pragma("unroll") for (int m = 0; m < 4; ++m) _Pragma("unroll") for (int k = 0; k < 2; ++k) dst[m][k] = *(const PG8_LAS bf16x8*)(lds + PG8_SA(b, h) + aoff + m * 2048 + k * 1024); } while (0)
; #define PG8_MMA(ai, bj, At, Bt) do { __builtin_amdgcn_s_setprio(1); _Pragma("unroll") for (int m = 0; m < 4; ++m) _Pragma("unroll") for (int n = 0; n < 2; ++n) _Pragma("unroll") for (int k = 0; k < 2; ++k) \
;         acc[ai][bj][m][n] = __builtin_amdgcn_mfma_f32_16x16x32_bf16(Bt[n][k], At[m][k], acc[ai][bj][m][n], 0, 0, 0); __builtin_amdgcn_s_setprio(0); } while (0)
; #define PG8_WAIT_V89() do { if constexpr (SLIVER) PG8_WAIT_V(9); else PG8_WAIT_V(8); } while (0)
; #define PG8_LDS_S(b) do { if constexpr (SLIVER) { Sf[0] = *(const PG8_LAS bf16x8*)(lds + STAGE_BYTES + (b) * 2048 + soff0); Sf[1] = *(const PG8_LAS bf16x8*)(lds + STAGE_BYTES + (b) * 2048 + (soff0 ^ 64)); } } while (0)
; #define PG8_WAIT_L(n) asm volatile("s_waitcnt lgkmcnt(" #n ")" ::: "memory")
; #define PG8_BAR __builtin_amdgcn_s_barrier()
; #define PG8_SCHED __builtin_amdgcn_sched_barrier(0)
; template <class Epi, class Sched, bool ALIGN_EPI = false, bool SP2 = false, bool SLIVER = false>
; __device__ __forceinline__ void gemm_phase(PG8_LAS unsigned char* lds, const Gemm g, const Sched& S, const Epi& E) {
;     ...
;             PG8_LDA(At, 1, 1); PG8_LDS_S(1); PG8_STAGE(PG8_SB(1, 0), b3, voffB); PG8_STAGE(PG8_SB(1, 1), b3 + hstep, voffB); PG8_STAGE(PG8_SA(1, 0), a3, voffA);
;             PG8_WAIT_V89(); PG8_WAIT_L(0); PG8_BAR; PG8_MMA(1, 0, At, B0); PG8_MMA(1, 1, At, B1); PG8_MMA_S(); PG8_BAR; PG8_SCHED;
	s_setprio 0
	s_add_i32 s78, 0, 0x20800
	s_add_i32 s77, s77, s18
	v_add_u32_e32 v178, s78, v213
	v_add_u32_e32 v184, s78, v214
	v_lshl_add_u64 v[208:209], v[202:203], 0, s[26:27]
	s_mov_b32 m0, s77
	ds_read_b128 v[2:5], v215 offset:49152
	ds_read_b128 v[6:9], v215 offset:50176
	ds_read_b128 v[216:219], v215 offset:51200
	ds_read_b128 v[220:223], v215 offset:52224
	ds_read_b128 v[224:227], v215 offset:53248
	ds_read_b128 v[228:231], v215 offset:54272
	ds_read_b128 v[232:235], v215 offset:55296
	ds_read_b128 v[240:243], v215 offset:56320
	ds_read_b128 v[180:183], v178
	ds_read_b128 v[184:187], v184
	global_load_lds_dwordx4 v[208:209], off
	v_lshl_add_u64 v[208:209], v[202:203], 0, s[28:29]
	s_add_i32 m0, s77, 0x2000
	s_add_i32 s77, s80, s18
	global_load_lds_dwordx4 v[208:209], off
	v_lshl_add_u64 v[208:209], v[202:203], 0, s[30:31]
	s_mov_b32 m0, s77
	v_lshl_add_u64 v[202:203], v[202:203], 0, s[34:35]
	global_load_lds_dwordx4 v[208:209], off
	s_add_i32 m0, s77, 0x2000
	s_nop 0
	global_load_lds_dwordx4 v[202:203], off
	v_lshl_add_u64 v[202:203], v[210:211], 0, s[26:27]
	s_mov_b32 m0, s10
	s_nop 0
	global_load_lds_dwordx4 v[202:203], off
	v_lshl_add_u64 v[202:203], v[210:211], 0, s[28:29]
	s_mov_b32 m0, s2
	s_nop 0
	global_load_lds_dwordx4 v[202:203], off
	s_waitcnt vmcnt(9)
	s_waitcnt lgkmcnt(0)
	s_setprio 1
	s_barrier
	v_mfma_f32_16x16x32_bf16 v[70:73], v[146:149], v[2:5], v[70:73]
	v_mfma_f32_16x16x32_bf16 v[70:73], v[150:153], v[6:9], v[70:73]
	v_mfma_f32_16x16x32_bf16 v[66:69], v[154:157], v[2:5], v[66:69]
	v_mfma_f32_16x16x32_bf16 v[66:69], v[158:161], v[6:9], v[66:69]
	v_mfma_f32_16x16x32_bf16 v[54:57], v[146:149], v[216:219], v[54:57]
	v_mfma_f32_16x16x32_bf16 v[54:57], v[150:153], v[220:223], v[54:57]
	v_mfma_f32_16x16x32_bf16 v[50:53], v[154:157], v[216:219], v[50:53]
	v_mfma_f32_16x16x32_bf16 v[50:53], v[158:161], v[220:223], v[50:53]
	v_mfma_f32_16x16x32_bf16 v[38:41], v[146:149], v[224:227], v[38:41]
	v_mfma_f32_16x16x32_bf16 v[38:41], v[150:153], v[228:231], v[38:41]
	v_mfma_f32_16x16x32_bf16 v[34:37], v[154:157], v[224:227], v[34:37]
	v_mfma_f32_16x16x32_bf16 v[34:37], v[158:161], v[228:231], v[34:37]
	v_mfma_f32_16x16x32_bf16 v[22:25], v[146:149], v[232:235], v[22:25]
	v_mfma_f32_16x16x32_bf16 v[22:25], v[150:153], v[240:243], v[22:25]
	v_mfma_f32_16x16x32_bf16 v[18:21], v[154:157], v[232:235], v[18:21]
	v_mfma_f32_16x16x32_bf16 v[18:21], v[158:161], v[240:243], v[18:21]
	s_setprio 0
	s_setprio 1
	v_mfma_f32_16x16x32_bf16 v[62:65], v[166:169], v[2:5], v[62:65]
	v_mfma_f32_16x16x32_bf16 v[62:65], v[170:173], v[6:9], v[62:65]
	v_mfma_f32_16x16x32_bf16 v[2:5], v[174:177], v[2:5], v[58:61]
	v_mfma_f32_16x16x32_bf16 v[58:61], v[162:165], v[6:9], v[2:5]
	v_mfma_f32_16x16x32_bf16 v[2:5], v[166:169], v[216:219], v[46:49]
	v_mfma_f32_16x16x32_bf16 v[46:49], v[170:173], v[220:223], v[2:5]
	v_mfma_f32_16x16x32_bf16 v[2:5], v[174:177], v[216:219], v[42:45]
	v_mfma_f32_16x16x32_bf16 v[42:45], v[162:165], v[220:223], v[2:5]
	v_mfma_f32_16x16x32_bf16 v[2:5], v[166:169], v[224:227], v[30:33]
	v_mfma_f32_16x16x32_bf16 v[30:33], v[170:173], v[228:231], v[2:5]
	v_mfma_f32_16x16x32_bf16 v[2:5], v[174:177], v[224:227], v[26:29]
	v_mfma_f32_16x16x32_bf16 v[26:29], v[162:165], v[228:231], v[2:5]
	v_mfma_f32_16x16x32_bf16 v[2:5], v[166:169], v[232:235], v[14:17]
	v_mfma_f32_16x16x32_bf16 v[14:17], v[170:173], v[240:243], v[2:5]
	v_mfma_f32_16x16x32_bf16 v[2:5], v[174:177], v[232:235], v[10:13]
	v_mfma_f32_16x16x32_bf16 v[10:13], v[162:165], v[240:243], v[2:5]
	s_setprio 0
	s_setprio 1
	s_and_b64 vcc, exec, s[52:53]
	s_cbranch_vccz .Lslv_c1
	v_mfma_f32_16x16x32_bf16 v[2:5], v[166:169], v[180:183], v[138:141]
	v_mfma_f32_16x16x32_bf16 v[6:9], v[170:173], v[184:187], v[2:5]
	v_mfma_f32_16x16x32_bf16 v[2:5], v[174:177], v[180:183], v[142:145]
	v_mfma_f32_16x16x32_bf16 v[2:5], v[162:165], v[184:187], v[2:5]
	s_branch .LBB0_597

; #define PG8_STAGE(bufoff, gbase, voff) do { _Pragma("unroll") for (int _i = 0; _i < 2; ++_i) \
;         __builtin_amdgcn_global_load_lds((const unsigned*)((const char*)(gbase) + (size_t)_i * qstep + (voff)[0]), (PG8_LAS unsigned*)(lds + (bufoff) + ldsw + _i * 8192), 16, 0, 0); } while (0)
; #define PG8_LDA(dst, b, h) do { _Pragma("unroll") for (int m = 0; m < 4; ++m) _Pragma("unroll") for (int k = 0; k < 2; ++k) dst[m][k] = *(const PG8_LAS bf16x8*)(lds + PG8_SA(b, h) + aoff + m * 2048 + k * 1024); } while (0)
; #define PG8_LDB(dst, b, h) do { _Pragma("unroll") for (int n = 0; n < 2; ++n) _Pragma("unroll") for (int k = 0; k < 2; ++k) dst[n][k] = *(const PG8_LAS bf16x8*)(lds + PG8_SB(b, h) + boff + n * 2048 + k * 1024); } while (0)
; #define PG8_MMA(ai, bj, At, Bt) do { __builtin_amdgcn_s_setprio(1); _Pragma("unroll") for (int m = 0; m < 4; ++m) _Pragma("unroll") for (int n = 0; n < 2; ++n) _Pragma("unroll") for (int k = 0; k < 2; ++k) \
;         acc[ai][bj][m][n] = __builtin_amdgcn_mfma_f32_16x16x32_bf16(Bt[n][k], At[m][k], acc[ai][bj][m][n], 0, 0, 0); __builtin_amdgcn_s_setprio(0); } while (0)
; #define PG8_WAIT_V89() do { if constexpr (SLIVER) PG8_WAIT_V(9); else PG8_WAIT_V(8); } while (0)
; #define PG8_WAIT_L(n) asm volatile("s_waitcnt lgkmcnt(" #n ")" ::: "memory")
; #define PG8_BAR __builtin_amdgcn_s_barrier()
; #define PG8_SCHED __builtin_amdgcn_sched_barrier(0)
; template <class Epi, class Sched, bool ALIGN_EPI = false, bool SP2 = false, bool SLIVER = false>
; __device__ __forceinline__ void gemm_phase(PG8_LAS unsigned char* lds, const Gemm g, const Sched& S, const Epi& E) {
;     ...
;             const bool last = (t == nt - 2);
;             const char* a1 = cA + (size_t)(t + 1) * kstep;
;             const char* a2 = last ? nA : cA + (size_t)(t + 2) * kstep; const char* b2 = last ? nB : cB + (size_t)(t + 2) * kstep;
;             const char* a3 = a2 + kstep; const char* b3 = b2 + kstep;
;             const char* s1 = cS + (size_t)(t + 1) * kstep; const char* s2 = last ? nS : cS + (size_t)(t + 2) * kstep;
;             if (last && has_next) S.a_ready(nxt);
;             if constexpr (SP2) {
;             PG8_LDB(B0, 0, 0); PG8_LDB(B1, 0, 1); PG8_SCHED; PG8_LDA(At, 0, 0); PG8_STAGE(PG8_SA(1, 1), a1 + hstep, voffA); PG8_STAGE_S(1, s1);
;             PG8_WAIT_V89(); PG8_WAIT_L(0); PG8_BAR; PG8_MMA(0, 0, At, B0); PG8_MMA(0, 1, At, B1); PG8_BAR; PG8_SCHED;
.LBB0_811:
	s_add_u32 s13, s90, s62
	s_addc_u32 s40, s91, s63
	s_add_u32 s13, s13, 0x100
	s_addc_u32 s66, s40, 0
	s_add_u32 s68, s2, s62
	s_addc_u32 s67, s3, s63
	s_add_i32 s69, 0, 0x10000
	s_cmpk_eq_i32 s62, 0x2b00
	s_cselect_b64 s[80:81], -1, 0
	s_and_b64 s[40:41], s[80:81], exec
	s_cselect_b32 s41, s85, s66
	s_cselect_b32 s40, s84, s13
	v_add_u32_e32 v66, s69, v220
	s_cselect_b32 s67, s87, s67
	s_cselect_b32 s66, s86, s68
	s_add_i32 s13, 0, 0x14000
	ds_read_b128 v[154:157], v66
	ds_read_b128 v[158:161], v66 offset:1024
	ds_read_b128 v[162:165], v66 offset:2048
	ds_read_b128 v[174:177], v66 offset:3072
	v_add_u32_e32 v66, s13, v220
	ds_read_b128 v[184:187], v66
	ds_read_b128 v[188:191], v66 offset:1024
	ds_read_b128 v[192:195], v66 offset:2048
	ds_read_b128 v[180:183], v66 offset:3072
	v_lshl_add_u64 v[146:147], v[214:215], 0, s[62:63]
	v_lshl_add_u64 v[148:149], v[146:147], 0, s[8:9]
	s_add_i32 m0, s19, 0xc000
	s_mov_b64 s[94:95], 0x210080
	ds_read_b128 v[66:69], v223
	ds_read_b128 v[70:73], v223 offset:1024
	ds_read_b128 v[74:77], v223 offset:2048
	ds_read_b128 v[78:81], v223 offset:3072
	ds_read_b128 v[216:219], v223 offset:4096
	ds_read_b128 v[224:227], v223 offset:5120
	ds_read_b128 v[228:231], v223 offset:6144
	ds_read_b128 v[232:235], v223 offset:7168
	global_load_lds_dwordx4 v[148:149], off
	v_lshl_add_u64 v[146:147], v[146:147], 0, s[94:95]
	s_add_i32 m0, s19, 0xe000
	s_nop 0
	global_load_lds_dwordx4 v[146:147], off
	v_lshl_add_u64 v[146:147], v[212:213], 0, s[62:63]
	s_add_i32 m0, s96, 0x20800
	s_nop 0
	global_load_lds_dword v[146:147], off
	s_waitcnt vmcnt(9)
	s_waitcnt lgkmcnt(0)
	s_setprio 1
	s_barrier
	v_mfma_f32_16x16x32_bf16 v[146:149], v[154:157], v[66:69], v[170:173]
	v_mfma_f32_16x16x32_bf16 v[146:149], v[158:161], v[70:73], v[146:149]
	v_mfma_f32_16x16x32_bf16 v[150:153], v[162:165], v[66:69], v[166:169]
	v_mfma_f32_16x16x32_bf16 v[150:153], v[174:177], v[70:73], v[150:153]
	v_mfma_f32_16x16x32_bf16 v[134:137], v[154:157], v[74:77], v[134:137]
	v_mfma_f32_16x16x32_bf16 v[134:137], v[158:161], v[78:81], v[134:137]
	v_mfma_f32_16x16x32_bf16 v[130:133], v[162:165], v[74:77], v[130:133]
	v_mfma_f32_16x16x32_bf16 v[130:133], v[174:177], v[78:81], v[130:133]
	v_mfma_f32_16x16x32_bf16 v[118:121], v[154:157], v[216:219], v[118:121]
	v_mfma_f32_16x16x32_bf16 v[118:121], v[158:161], v[224:227], v[118:121]
	v_mfma_f32_16x16x32_bf16 v[114:117], v[162:165], v[216:219], v[114:117]
	v_mfma_f32_16x16x32_bf16 v[114:117], v[174:177], v[224:227], v[114:117]
	v_mfma_f32_16x16x32_bf16 v[102:105], v[154:157], v[228:231], v[102:105]
	v_mfma_f32_16x16x32_bf16 v[102:105], v[158:161], v[232:235], v[102:105]
	v_mfma_f32_16x16x32_bf16 v[98:101], v[162:165], v[228:231], v[98:101]
	v_mfma_f32_16x16x32_bf16 v[98:101], v[174:177], v[232:235], v[98:101]
	s_setprio 0
	s_setprio 1
	v_mfma_f32_16x16x32_bf16 v[142:145], v[184:187], v[66:69], v[142:145]
	v_mfma_f32_16x16x32_bf16 v[142:145], v[188:191], v[70:73], v[142:145]
	v_mfma_f32_16x16x32_bf16 v[66:69], v[192:195], v[66:69], v[138:141]
	v_mfma_f32_16x16x32_bf16 v[138:141], v[180:183], v[70:73], v[66:69]
	v_mfma_f32_16x16x32_bf16 v[66:69], v[184:187], v[74:77], v[126:129]
	v_mfma_f32_16x16x32_bf16 v[126:129], v[188:191], v[78:81], v[66:69]
	v_mfma_f32_16x16x32_bf16 v[66:69], v[192:195], v[74:77], v[122:125]
	v_mfma_f32_16x16x32_bf16 v[122:125], v[180:183], v[78:81], v[66:69]
	v_mfma_f32_16x16x32_bf16 v[66:69], v[184:187], v[216:219], v[110:113]
	v_mfma_f32_16x16x32_bf16 v[110:113], v[188:191], v[224:227], v[66:69]
	v_mfma_f32_16x16x32_bf16 v[66:69], v[192:195], v[216:219], v[106:109]
	v_mfma_f32_16x16x32_bf16 v[106:109], v[180:183], v[224:227], v[66:69]
	v_mfma_f32_16x16x32_bf16 v[66:69], v[184:187], v[228:231], v[94:97]
	v_mfma_f32_16x16x32_bf16 v[94:97], v[188:191], v[232:235], v[66:69]
	v_mfma_f32_16x16x32_bf16 v[66:69], v[192:195], v[228:231], v[90:93]
	v_mfma_f32_16x16x32_bf16 v[90:93], v[180:183], v[232:235], v[66:69]
	s_barrier
; #define PG8_SB(B) __builtin_amdgcn_rcpf(1.f + expneg(B))
; #define PG8_SB(B) __builtin_amdgcn_rcpf(1.f + expneg(B))
; #define PG8_STAGE(bufoff, gbase, voff) do { _Pragma("unroll") for (int _i = 0; _i < 2; ++_i) \
;         __builtin_amdgcn_global_load_lds((const unsigned*)((const char*)(gbase) + (size_t)_i * qstep + (voff)[0]), (PG8_LAS unsigned*)(lds + (bufoff) + ldsw + _i * 8192), 16, 0, 0); } while (0)
; #define PG8_LDA(dst, b, h) do { _Pragma("unroll") for (int m = 0; m < 4; ++m) _Pragma("unroll") for (int k = 0; k < 2; ++k) dst[m][k] = *(const PG8_LAS bf16x8*)(lds + PG8_SA(b, h) + aoff + m * 2048 + k * 1024); } while (0)
; #define PG8_MMA(ai, bj, At, Bt) do { __builtin_amdgcn_s_setprio(1); _Pragma("unroll") for (int m = 0; m < 4; ++m) _Pragma("unroll") for (int n = 0; n < 2; ++n) _Pragma("unroll") for (int k = 0; k < 2; ++k) \
;         acc[ai][bj][m][n] = __builtin_amdgcn_mfma_f32_16x16x32_bf16(Bt[n][k], At[m][k], acc[ai][bj][m][n], 0, 0, 0); __builtin_amdgcn_s_setprio(0); } while (0)
; #define PG8_WAIT_V89() do { if constexpr (SLIVER) PG8_WAIT_V(9); else PG8_WAIT_V(8); } while (0)
; #define PG8_LDS_S(b) do { if constexpr (SLIVER) { Sf[0] = *(const PG8_LAS bf16x8*)(lds + STAGE_BYTES + (b) * 2048 + soff0); Sf[1] = *(const PG8_LAS bf16x8*)(lds + STAGE_BYTES + (b) * 2048 + (soff0 ^ 64)); } } while (0)
; #define PG8_WAIT_L(n) asm volatile("s_waitcnt lgkmcnt(" #n ")" ::: "memory")
; #define PG8_BAR __builtin_amdgcn_s_barrier()
; #define PG8_SCHED __builtin_amdgcn_sched_barrier(0)
; template <class Epi, class Sched, bool ALIGN_EPI = false, bool SP2 = false, bool SLIVER = false>
; __device__ __forceinline__ void gemm_phase(PG8_LAS unsigned char* lds, const Gemm g, const Sched& S, const Epi& E) {
;     ...
;             PG8_LDA(At, 0, 1); PG8_LDS_S(0); PG8_STAGE(PG8_SB(0, 0), b2, voffB); PG8_STAGE(PG8_SB(0, 1), b2 + hstep, voffB); PG8_STAGE(PG8_SA(0, 0), a2, voffA);
;             PG8_WAIT_V89(); PG8_WAIT_L(0); PG8_BAR; PG8_MMA(1, 0, At, B0); PG8_MMA(1, 1, At, B1); PG8_MMA_S(); PG8_BAR; PG8_SCHED;
	s_setprio 0
	s_add_i32 s68, 0, 0x20000
	v_lshl_add_u64 v[216:217], s[66:67], 0, v[198:199]
	s_add_i32 s66, s69, s18
	v_add_u32_e32 v74, s68, v221
	v_add_u32_e32 v75, s68, v222
	s_mov_b32 m0, s66
	ds_read_b128 v[66:69], v223 offset:16384
	ds_read_b128 v[70:73], v223 offset:17408
	ds_read_b128 v[224:227], v223 offset:18432
	ds_read_b128 v[228:231], v223 offset:19456
	ds_read_b128 v[232:235], v223 offset:20480
	ds_read_b128 v[240:243], v223 offset:21504
	ds_read_b128 v[244:247], v223 offset:22528
	ds_read_b128 v[248:251], v223 offset:23552
	ds_read_b128 v[166:169], v74
	ds_read_b128 v[170:173], v75
	global_load_lds_dwordx4 v[216:217], off
	v_lshl_add_u64 v[74:75], v[216:217], 0, s[64:65]
	s_add_i32 m0, s66, 0x2000
	s_add_i32 s13, s13, s18
	global_load_lds_dwordx4 v[74:75], off
	v_lshl_add_u64 v[74:75], v[216:217], 0, s[0:1]
	s_mov_b32 m0, s13
	v_lshl_add_u64 v[218:219], s[40:41], 0, v[196:197]
	global_load_lds_dwordx4 v[74:75], off
	v_lshl_add_u64 v[74:75], v[216:217], 0, s[74:75]
	s_add_i32 m0, s13, 0x2000
	s_nop 0
	global_load_lds_dwordx4 v[74:75], off
	s_mov_b32 m0, s19
	v_lshl_add_u64 v[74:75], v[218:219], 0, s[64:65]
	global_load_lds_dwordx4 v[218:219], off
	s_mov_b32 m0, s52
	s_nop 0
	global_load_lds_dwordx4 v[74:75], off
	s_waitcnt vmcnt(9)
	s_waitcnt lgkmcnt(0)
	s_setprio 1
	s_barrier
	v_mfma_f32_16x16x32_bf16 v[74:77], v[154:157], v[66:69], v[86:89]
	v_mfma_f32_16x16x32_bf16 v[74:77], v[158:161], v[70:73], v[74:77]
	v_mfma_f32_16x16x32_bf16 v[78:81], v[162:165], v[66:69], v[82:85]
	v_mfma_f32_16x16x32_bf16 v[78:81], v[174:177], v[70:73], v[78:81]
	v_mfma_f32_16x16x32_bf16 v[54:57], v[154:157], v[224:227], v[54:57]
	v_mfma_f32_16x16x32_bf16 v[54:57], v[158:161], v[228:231], v[54:57]
	v_mfma_f32_16x16x32_bf16 v[50:53], v[162:165], v[224:227], v[50:53]
	v_mfma_f32_16x16x32_bf16 v[50:53], v[174:177], v[228:231], v[50:53]
	v_mfma_f32_16x16x32_bf16 v[38:41], v[154:157], v[232:235], v[38:41]
	v_mfma_f32_16x16x32_bf16 v[38:41], v[158:161], v[240:243], v[38:41]
	v_mfma_f32_16x16x32_bf16 v[34:37], v[162:165], v[232:235], v[34:37]
	v_mfma_f32_16x16x32_bf16 v[34:37], v[174:177], v[240:243], v[34:37]
	v_mfma_f32_16x16x32_bf16 v[22:25], v[154:157], v[244:247], v[22:25]
	v_mfma_f32_16x16x32_bf16 v[22:25], v[158:161], v[248:251], v[22:25]
	v_mfma_f32_16x16x32_bf16 v[18:21], v[162:165], v[244:247], v[18:21]
	v_mfma_f32_16x16x32_bf16 v[18:21], v[174:177], v[248:251], v[18:21]
	s_setprio 0
	s_setprio 1
	v_mfma_f32_16x16x32_bf16 v[62:65], v[184:187], v[66:69], v[62:65]
	v_mfma_f32_16x16x32_bf16 v[62:65], v[188:191], v[70:73], v[62:65]
	v_mfma_f32_16x16x32_bf16 v[58:61], v[192:195], v[66:69], v[58:61]
	v_mfma_f32_16x16x32_bf16 v[58:61], v[180:183], v[70:73], v[58:61]
	v_mfma_f32_16x16x32_bf16 v[46:49], v[184:187], v[224:227], v[46:49]
	v_mfma_f32_16x16x32_bf16 v[46:49], v[188:191], v[228:231], v[46:49]
	v_mfma_f32_16x16x32_bf16 v[42:45], v[192:195], v[224:227], v[42:45]
	v_mfma_f32_16x16x32_bf16 v[42:45], v[180:183], v[228:231], v[42:45]
	v_mfma_f32_16x16x32_bf16 v[30:33], v[184:187], v[232:235], v[30:33]
	v_mfma_f32_16x16x32_bf16 v[30:33], v[188:191], v[240:243], v[30:33]
	v_mfma_f32_16x16x32_bf16 v[26:29], v[192:195], v[232:235], v[26:29]
	v_mfma_f32_16x16x32_bf16 v[26:29], v[180:183], v[240:243], v[26:29]
	v_mfma_f32_16x16x32_bf16 v[14:17], v[184:187], v[244:247], v[14:17]
	v_mfma_f32_16x16x32_bf16 v[14:17], v[188:191], v[248:251], v[14:17]
	v_mfma_f32_16x16x32_bf16 v[10:13], v[192:195], v[244:247], v[10:13]
	v_mfma_f32_16x16x32_bf16 v[10:13], v[180:183], v[248:251], v[10:13]
	s_setprio 0
	s_setprio 1
	s_and_b64 vcc, exec, s[82:83]
	s_cbranch_vccz .Lslv_b2
	v_mfma_f32_16x16x32_bf16 v[66:69], v[184:187], v[166:169], v[6:9]
	v_mfma_f32_16x16x32_bf16 v[70:73], v[192:195], v[166:169], v[2:5]
	v_mfma_f32_16x16x32_bf16 v[66:69], v[188:191], v[170:173], v[66:69]
	v_mfma_f32_16x16x32_bf16 v[70:73], v[180:183], v[170:173], v[70:73]
	s_branch .LBB0_815

; #define PG8_STAGE(bufoff, gbase, voff) do { _Pragma("unroll") for (int _i = 0; _i < 2; ++_i) \
;         __builtin_amdgcn_global_load_lds((const unsigned*)((const char*)(gbase) + (size_t)_i * qstep + (voff)[0]), (PG8_LAS unsigned*)(lds + (bufoff) + ldsw + _i * 8192), 16, 0, 0); } while (0)
; #define PG8_LDA(dst, b, h) do { _Pragma("unroll") for (int m = 0; m < 4; ++m) _Pragma("unroll") for (int k = 0; k < 2; ++k) dst[m][k] = *(const PG8_LAS bf16x8*)(lds + PG8_SA(b, h) + aoff + m * 2048 + k * 1024); } while (0)
; #define PG8_LDB(dst, b, h) do { _Pragma("unroll") for (int n = 0; n < 2; ++n) _Pragma("unroll") for (int k = 0; k < 2; ++k) dst[n][k] = *(const PG8_LAS bf16x8*)(lds + PG8_SB(b, h) + boff + n * 2048 + k * 1024); } while (0)
; #define PG8_MMA(ai, bj, At, Bt) do { __builtin_amdgcn_s_setprio(1); _Pragma("unroll") for (int m = 0; m < 4; ++m) _Pragma("unroll") for (int n = 0; n < 2; ++n) _Pragma("unroll") for (int k = 0; k < 2; ++k) \
;         acc[ai][bj][m][n] = __builtin_amdgcn_mfma_f32_16x16x32_bf16(Bt[n][k], At[m][k], acc[ai][bj][m][n], 0, 0, 0); __builtin_amdgcn_s_setprio(0); } while (0)
; #define PG8_WAIT_V89() do { if constexpr (SLIVER) PG8_WAIT_V(9); else PG8_WAIT_V(8); } while (0)
; #define PG8_STAGE_S(b, gbase) do { if constexpr (SLIVER) __builtin_amdgcn_global_load_lds((const unsigned*)((const char*)(gbase) + voffS), (PG8_LAS unsigned*)(lds + STAGE_BYTES + (b) * 2048 + wid * 256), 4, 0, 0); } while (0)
; #define PG8_WAIT_L(n) asm volatile("s_waitcnt lgkmcnt(" #n ")" ::: "memory")
; #define PG8_BAR __builtin_amdgcn_s_barrier()
; #define PG8_SCHED __builtin_amdgcn_sched_barrier(0)
; template <class Epi, class Sched, bool ALIGN_EPI = false, bool SP2 = false, bool SLIVER = false>
; __device__ __forceinline__ void gemm_phase(PG8_LAS unsigned char* lds, const Gemm g, const Sched& S, const Epi& E) {
;     ...
;             PG8_LDB(B0, 1, 0); PG8_LDB(B1, 1, 1); PG8_SCHED; PG8_LDA(At, 1, 0); PG8_STAGE(PG8_SA(0, 1), a2 + hstep, voffA); PG8_STAGE_S(0, s2);
;             PG8_WAIT_V89(); PG8_WAIT_L(0); PG8_BAR; PG8_MMA(0, 0, At, B0); PG8_MMA(0, 1, At, B1); PG8_BAR; PG8_SCHED;
.LBB0_815:
	s_barrier
	s_setprio 0
	s_add_u32 s13, s92, s62
	s_addc_u32 s66, s93, s63
	s_add_u32 s13, s13, 0x100
	s_addc_u32 s68, s66, 0
	s_and_b64 s[66:67], s[80:81], exec
	s_cselect_b32 s67, s89, s68
	s_cselect_b32 s66, s88, s13
	s_add_i32 s13, 0, 0x18000
	v_add_u32_e32 v2, s13, v220
	s_add_i32 s68, 0, 0x1c000
	ds_read_b128 v[154:157], v2
	ds_read_b128 v[158:161], v2 offset:1024
	ds_read_b128 v[162:165], v2 offset:2048
	ds_read_b128 v[174:177], v2 offset:3072
	v_add_u32_e32 v2, s68, v220
	ds_read_b128 v[184:187], v2
	ds_read_b128 v[188:191], v2 offset:1024
	ds_read_b128 v[192:195], v2 offset:2048
	ds_read_b128 v[180:183], v2 offset:3072
	s_mov_b32 m0, s53
	v_lshl_add_u64 v[166:167], v[218:219], 0, s[0:1]
	ds_read_b128 v[2:5], v223 offset:32768
	ds_read_b128 v[6:9], v223 offset:33792
	ds_read_b128 v[82:85], v223 offset:34816
	ds_read_b128 v[86:89], v223 offset:35840
	ds_read_b128 v[224:227], v223 offset:36864
	ds_read_b128 v[228:231], v223 offset:37888
	ds_read_b128 v[232:235], v223 offset:38912
	ds_read_b128 v[240:243], v223 offset:39936
	global_load_lds_dwordx4 v[166:167], off
	v_lshl_add_u64 v[166:167], v[218:219], 0, s[74:75]
	s_mov_b32 m0, s54
	s_nop 0
	global_load_lds_dwordx4 v[166:167], off
	v_lshl_add_u64 v[166:167], s[66:67], 0, v[200:201]
	s_mov_b32 m0, s55
	s_nop 0
	global_load_lds_dword v[166:167], off
	s_waitcnt vmcnt(9)
	s_waitcnt lgkmcnt(0)
	s_setprio 1
	s_barrier
	v_mfma_f32_16x16x32_bf16 v[146:149], v[154:157], v[2:5], v[146:149]
	v_mfma_f32_16x16x32_bf16 v[170:173], v[158:161], v[6:9], v[146:149]
	v_mfma_f32_16x16x32_bf16 v[146:149], v[162:165], v[2:5], v[150:153]
	v_mfma_f32_16x16x32_bf16 v[166:169], v[174:177], v[6:9], v[146:149]
	v_mfma_f32_16x16x32_bf16 v[134:137], v[154:157], v[82:85], v[134:137]
	v_mfma_f32_16x16x32_bf16 v[134:137], v[158:161], v[86:89], v[134:137]
	v_mfma_f32_16x16x32_bf16 v[130:133], v[162:165], v[82:85], v[130:133]
	v_mfma_f32_16x16x32_bf16 v[130:133], v[174:177], v[86:89], v[130:133]
	v_mfma_f32_16x16x32_bf16 v[118:121], v[154:157], v[224:227], v[118:121]
	v_mfma_f32_16x16x32_bf16 v[118:121], v[158:161], v[228:231], v[118:121]
	v_mfma_f32_16x16x32_bf16 v[114:117], v[162:165], v[224:227], v[114:117]
	v_mfma_f32_16x16x32_bf16 v[114:117], v[174:177], v[228:231], v[114:117]
	v_mfma_f32_16x16x32_bf16 v[102:105], v[154:157], v[232:235], v[102:105]
	v_mfma_f32_16x16x32_bf16 v[102:105], v[158:161], v[240:243], v[102:105]
	v_mfma_f32_16x16x32_bf16 v[98:101], v[162:165], v[232:235], v[98:101]
	v_mfma_f32_16x16x32_bf16 v[98:101], v[174:177], v[240:243], v[98:101]
	s_setprio 0
	s_setprio 1
	v_mfma_f32_16x16x32_bf16 v[142:145], v[184:187], v[2:5], v[142:145]
	v_mfma_f32_16x16x32_bf16 v[142:145], v[188:191], v[6:9], v[142:145]
	v_mfma_f32_16x16x32_bf16 v[2:5], v[192:195], v[2:5], v[138:141]
	v_mfma_f32_16x16x32_bf16 v[138:141], v[180:183], v[6:9], v[2:5]
	v_mfma_f32_16x16x32_bf16 v[2:5], v[184:187], v[82:85], v[126:129]
	v_mfma_f32_16x16x32_bf16 v[126:129], v[188:191], v[86:89], v[2:5]
	v_mfma_f32_16x16x32_bf16 v[2:5], v[192:195], v[82:85], v[122:125]
	v_mfma_f32_16x16x32_bf16 v[122:125], v[180:183], v[86:89], v[2:5]
	v_mfma_f32_16x16x32_bf16 v[2:5], v[184:187], v[224:227], v[110:113]
	v_mfma_f32_16x16x32_bf16 v[110:113], v[188:191], v[228:231], v[2:5]
	v_mfma_f32_16x16x32_bf16 v[2:5], v[192:195], v[224:227], v[106:109]
	v_mfma_f32_16x16x32_bf16 v[106:109], v[180:183], v[228:231], v[2:5]
	v_mfma_f32_16x16x32_bf16 v[2:5], v[184:187], v[232:235], v[94:97]
	v_mfma_f32_16x16x32_bf16 v[94:97], v[188:191], v[240:243], v[2:5]
	v_mfma_f32_16x16x32_bf16 v[2:5], v[192:195], v[232:235], v[90:93]
	v_mfma_f32_16x16x32_bf16 v[90:93], v[180:183], v[240:243], v[2:5]
	s_barrier
; #define PG8_SB(B) __builtin_amdgcn_rcpf(1.f + expneg(B))
; #define PG8_SB(B) __builtin_amdgcn_rcpf(1.f + expneg(B))
; #define PG8_STAGE(bufoff, gbase, voff) do { _Pragma("unroll") for (int _i = 0; _i < 2; ++_i) \
;         __builtin_amdgcn_global_load_lds((const unsigned*)((const char*)(gbase) + (size_t)_i * qstep + (voff)[0]), (PG8_LAS unsigned*)(lds + (bufoff) + ldsw + _i * 8192), 16, 0, 0); } while (0)
; #define PG8_LDA(dst, b, h) do { _Pragma("unroll") for (int m = 0; m < 4; ++m) _Pragma("unroll") for (int k = 0; k < 2; ++k) dst[m][k] = *(const PG8_LAS bf16x8*)(lds + PG8_SA(b, h) + aoff + m * 2048 + k * 1024); } while (0)
; #define PG8_MMA(ai, bj, At, Bt) do { __builtin_amdgcn_s_setprio(1); _Pragma("unroll") for (int m = 0; m < 4; ++m) _Pragma("unroll") for (int n = 0; n < 2; ++n) _Pragma("unroll") for (int k = 0; k < 2; ++k) \
;         acc[ai][bj][m][n] = __builtin_amdgcn_mfma_f32_16x16x32_bf16(Bt[n][k], At[m][k], acc[ai][bj][m][n], 0, 0, 0); __builtin_amdgcn_s_setprio(0); } while (0)
; #define PG8_WAIT_V89() do { if constexpr (SLIVER) PG8_WAIT_V(9); else PG8_WAIT_V(8); } while (0)
; #define PG8_LDS_S(b) do { if constexpr (SLIVER) { Sf[0] = *(const PG8_LAS bf16x8*)(lds + STAGE_BYTES + (b) * 2048 + soff0); Sf[1] = *(const PG8_LAS bf16x8*)(lds + STAGE_BYTES + (b) * 2048 + (soff0 ^ 64)); } } while (0)
; #define PG8_WAIT_L(n) asm volatile("s_waitcnt lgkmcnt(" #n ")" ::: "memory")
; #define PG8_BAR __builtin_amdgcn_s_barrier()
; #define PG8_SCHED __builtin_amdgcn_sched_barrier(0)
; template <class Epi, class Sched, bool ALIGN_EPI = false, bool SP2 = false, bool SLIVER = false>
; __device__ __forceinline__ void gemm_phase(PG8_LAS unsigned char* lds, const Gemm g, const Sched& S, const Epi& E) {
;     ...
;             PG8_LDA(At, 1, 1); PG8_LDS_S(1); PG8_STAGE(PG8_SB(1, 0), b3, voffB); PG8_STAGE(PG8_SB(1, 1), b3 + hstep, voffB); PG8_STAGE(PG8_SA(1, 0), a3, voffA);
;             PG8_WAIT_V89(); PG8_WAIT_L(0); PG8_BAR; PG8_MMA(1, 0, At, B0); PG8_MMA(1, 1, At, B1); PG8_MMA_S(); PG8_BAR; PG8_SCHED;
	s_setprio 0
	s_add_i32 s66, 0, 0x20800
	v_add_u32_e32 v82, s66, v221
	v_add_u32_e32 v83, s66, v222
	s_add_i32 s13, s13, s18
	ds_read_b128 v[2:5], v223 offset:49152
	ds_read_b128 v[6:9], v223 offset:50176
	ds_read_b128 v[224:227], v223 offset:51200
	ds_read_b128 v[228:231], v223 offset:52224
	ds_read_b128 v[232:235], v223 offset:53248
	ds_read_b128 v[240:243], v223 offset:54272
	ds_read_b128 v[244:247], v223 offset:55296
	ds_read_b128 v[248:251], v223 offset:56320
	ds_read_b128 v[146:149], v82
	ds_read_b128 v[150:153], v83
	v_lshl_add_u64 v[82:83], v[216:217], 0, s[26:27]
	s_mov_b32 m0, s13
	s_mov_b64 s[66:67], 0x210080
	global_load_lds_dwordx4 v[82:83], off
	v_lshl_add_u64 v[82:83], v[216:217], 0, s[60:61]
	s_add_i32 m0, s13, 0x2000
	s_add_i32 s13, s68, s18
	global_load_lds_dwordx4 v[82:83], off
	v_lshl_add_u64 v[82:83], v[216:217], 0, s[8:9]
	s_mov_b32 m0, s13
	s_nop 0
	global_load_lds_dwordx4 v[82:83], off
	v_lshl_add_u64 v[82:83], v[216:217], 0, s[66:67]
	s_add_i32 m0, s13, 0x2000
	s_nop 0
	global_load_lds_dwordx4 v[82:83], off
	v_lshl_add_u64 v[82:83], v[218:219], 0, s[26:27]
	s_mov_b32 m0, s10
	s_nop 0
	global_load_lds_dwordx4 v[82:83], off
	v_lshl_add_u64 v[82:83], v[218:219], 0, s[60:61]
	s_mov_b32 m0, s48
	s_nop 0
	global_load_lds_dwordx4 v[82:83], off
	s_waitcnt vmcnt(9)
	s_waitcnt lgkmcnt(0)
	s_setprio 1
	s_barrier
	v_mfma_f32_16x16x32_bf16 v[74:77], v[154:157], v[2:5], v[74:77]
	v_mfma_f32_16x16x32_bf16 v[86:89], v[158:161], v[6:9], v[74:77]
	v_mfma_f32_16x16x32_bf16 v[74:77], v[162:165], v[2:5], v[78:81]
	v_mfma_f32_16x16x32_bf16 v[82:85], v[174:177], v[6:9], v[74:77]
	v_mfma_f32_16x16x32_bf16 v[54:57], v[154:157], v[224:227], v[54:57]
	v_mfma_f32_16x16x32_bf16 v[54:57], v[158:161], v[228:231], v[54:57]
	v_mfma_f32_16x16x32_bf16 v[50:53], v[162:165], v[224:227], v[50:53]
	v_mfma_f32_16x16x32_bf16 v[50:53], v[174:177], v[228:231], v[50:53]
	v_mfma_f32_16x16x32_bf16 v[38:41], v[154:157], v[232:235], v[38:41]
	v_mfma_f32_16x16x32_bf16 v[38:41], v[158:161], v[240:243], v[38:41]
	v_mfma_f32_16x16x32_bf16 v[34:37], v[162:165], v[232:235], v[34:37]
	v_mfma_f32_16x16x32_bf16 v[34:37], v[174:177], v[240:243], v[34:37]
	v_mfma_f32_16x16x32_bf16 v[22:25], v[154:157], v[244:247], v[22:25]
	v_mfma_f32_16x16x32_bf16 v[22:25], v[158:161], v[248:251], v[22:25]
	v_mfma_f32_16x16x32_bf16 v[18:21], v[162:165], v[244:247], v[18:21]
	v_mfma_f32_16x16x32_bf16 v[18:21], v[174:177], v[248:251], v[18:21]
	s_setprio 0
	s_setprio 1
	v_mfma_f32_16x16x32_bf16 v[62:65], v[184:187], v[2:5], v[62:65]
	v_mfma_f32_16x16x32_bf16 v[62:65], v[188:191], v[6:9], v[62:65]
	v_mfma_f32_16x16x32_bf16 v[2:5], v[192:195], v[2:5], v[58:61]
	v_mfma_f32_16x16x32_bf16 v[58:61], v[180:183], v[6:9], v[2:5]
	v_mfma_f32_16x16x32_bf16 v[2:5], v[184:187], v[224:227], v[46:49]
	v_mfma_f32_16x16x32_bf16 v[46:49], v[188:191], v[228:231], v[2:5]
	v_mfma_f32_16x16x32_bf16 v[2:5], v[192:195], v[224:227], v[42:45]
	v_mfma_f32_16x16x32_bf16 v[42:45], v[180:183], v[228:231], v[2:5]
	v_mfma_f32_16x16x32_bf16 v[2:5], v[184:187], v[232:235], v[30:33]
	v_mfma_f32_16x16x32_bf16 v[30:33], v[188:191], v[240:243], v[2:5]
	v_mfma_f32_16x16x32_bf16 v[2:5], v[192:195], v[232:235], v[26:29]
	v_mfma_f32_16x16x32_bf16 v[26:29], v[180:183], v[240:243], v[2:5]
	v_mfma_f32_16x16x32_bf16 v[2:5], v[184:187], v[244:247], v[14:17]
	v_mfma_f32_16x16x32_bf16 v[14:17], v[188:191], v[248:251], v[2:5]
	v_mfma_f32_16x16x32_bf16 v[2:5], v[192:195], v[244:247], v[10:13]
	v_mfma_f32_16x16x32_bf16 v[10:13], v[180:183], v[248:251], v[2:5]
	s_setprio 0
	s_setprio 1
	s_and_b64 vcc, exec, s[82:83]
	s_cbranch_vccz .Lslv_c2
	v_mfma_f32_16x16x32_bf16 v[2:5], v[184:187], v[146:149], v[66:69]
	v_mfma_f32_16x16x32_bf16 v[6:9], v[188:191], v[150:153], v[2:5]
	v_mfma_f32_16x16x32_bf16 v[2:5], v[192:195], v[146:149], v[70:73]
	v_mfma_f32_16x16x32_bf16 v[2:5], v[180:183], v[150:153], v[2:5]
	s_branch .LBB0_810

; #define PG8_STAGE(bufoff, gbase, voff) do { _Pragma("unroll") for (int _i = 0; _i < 2; ++_i) \
;         __builtin_amdgcn_global_load_lds((const unsigned*)((const char*)(gbase) + (size_t)_i * qstep + (voff)[0]), (PG8_LAS unsigned*)(lds + (bufoff) + ldsw + _i * 8192), 16, 0, 0); } while (0)
; #define PG8_LDA(dst, b, h) do { _Pragma("unroll") for (int m = 0; m < 4; ++m) _Pragma("unroll") for (int k = 0; k < 2; ++k) dst[m][k] = *(const PG8_LAS bf16x8*)(lds + PG8_SA(b, h) + aoff + m * 2048 + k * 1024); } while (0)
; #define PG8_LDB(dst, b, h) do { _Pragma("unroll") for (int n = 0; n < 2; ++n) _Pragma("unroll") for (int k = 0; k < 2; ++k) dst[n][k] = *(const PG8_LAS bf16x8*)(lds + PG8_SB(b, h) + boff + n * 2048 + k * 1024); } while (0)
; #define PG8_MMA(ai, bj, At, Bt) do { __builtin_amdgcn_s_setprio(1); _Pragma("unroll") for (int m = 0; m < 4; ++m) _Pragma("unroll") for (int n = 0; n < 2; ++n) _Pragma("unroll") for (int k = 0; k < 2; ++k) \
;         acc[ai][bj][m][n] = __builtin_amdgcn_mfma_f32_16x16x32_bf16(Bt[n][k], At[m][k], acc[ai][bj][m][n], 0, 0, 0); __builtin_amdgcn_s_setprio(0); } while (0)
; #define PG8_WAIT_V89() do { if constexpr (SLIVER) PG8_WAIT_V(9); else PG8_WAIT_V(8); } while (0)
; #define PG8_STAGE_S(b, gbase) do { if constexpr (SLIVER) __builtin_amdgcn_global_load_lds((const unsigned*)((const char*)(gbase) + voffS), (PG8_LAS unsigned*)(lds + STAGE_BYTES + (b) * 2048 + wid * 256), 4, 0, 0); } while (0)
; #define PG8_WAIT_L(n) asm volatile("s_waitcnt lgkmcnt(" #n ")" ::: "memory")
; #define PG8_BAR __builtin_amdgcn_s_barrier()
; #define PG8_SCHED __builtin_amdgcn_sched_barrier(0)
; template <class Epi, class Sched, bool ALIGN_EPI = false, bool SP2 = false, bool SLIVER = false>
; __device__ __forceinline__ void gemm_phase(PG8_LAS unsigned char* lds, const Gemm g, const Sched& S, const Epi& E) {
;     ...
;             PG8_LDB(B0, 1, 0); PG8_LDB(B1, 1, 1); PG8_SCHED; PG8_LDA(At, 1, 0); PG8_STAGE(PG8_SA(0, 1), a2 + hstep, voffA); PG8_STAGE_S(0, s2);
;             PG8_WAIT_V89(); PG8_WAIT_L(0); PG8_BAR; PG8_MMA(0, 0, At, B0); PG8_MMA(0, 1, At, B1); PG8_BAR; PG8_SCHED;
.LBB0_938:
	s_barrier
	s_setprio 0
	s_add_u32 s12, s54, s62
	s_addc_u32 s13, s55, s63
	s_add_u32 s68, s12, 0x100
	s_addc_u32 s69, s13, 0
	s_and_b64 s[12:13], s[80:81], exec
	s_cselect_b32 s13, s19, s69
	s_cselect_b32 s12, s18, s68
	s_add_i32 s68, 0, 0x18000
	v_add_u32_e32 v2, s68, v212
	s_add_i32 s69, 0, 0x1c000
	ds_read_b128 v[146:149], v2
	ds_read_b128 v[150:153], v2 offset:1024
	ds_read_b128 v[154:157], v2 offset:2048
	ds_read_b128 v[158:161], v2 offset:3072
	v_add_u32_e32 v2, s69, v212
	ds_read_b128 v[166:169], v2
	ds_read_b128 v[170:173], v2 offset:1024
	ds_read_b128 v[174:177], v2 offset:2048
	ds_read_b128 v[162:165], v2 offset:3072
	s_mov_b32 m0, s49
	v_lshl_add_u64 v[208:209], v[210:211], 0, s[46:47]
	ds_read_b128 v[2:5], v215 offset:32768
	ds_read_b128 v[6:9], v215 offset:33792
	ds_read_b128 v[180:183], v215 offset:34816
	ds_read_b128 v[184:187], v215 offset:35840
	ds_read_b128 v[216:219], v215 offset:36864
	ds_read_b128 v[220:223], v215 offset:37888
	ds_read_b128 v[224:227], v215 offset:38912
	ds_read_b128 v[228:231], v215 offset:39936
	global_load_lds_dwordx4 v[208:209], off
	v_lshl_add_u64 v[208:209], v[210:211], 0, s[6:7]
	s_mov_b32 m0, s88
	s_nop 0
	global_load_lds_dwordx4 v[208:209], off
	v_lshl_add_u64 v[208:209], s[12:13], 0, v[192:193]
	s_mov_b32 m0, s89
	s_nop 0
	global_load_lds_dword v[208:209], off
	s_waitcnt vmcnt(9)
	s_waitcnt lgkmcnt(0)
	s_setprio 1
	s_barrier
	v_mfma_f32_16x16x32_bf16 v[134:137], v[146:149], v[2:5], v[134:137]
	v_mfma_f32_16x16x32_bf16 v[134:137], v[150:153], v[6:9], v[134:137]
	v_mfma_f32_16x16x32_bf16 v[130:133], v[154:157], v[2:5], v[130:133]
	v_mfma_f32_16x16x32_bf16 v[130:133], v[158:161], v[6:9], v[130:133]
	v_mfma_f32_16x16x32_bf16 v[126:129], v[146:149], v[180:183], v[126:129]
	v_mfma_f32_16x16x32_bf16 v[126:129], v[150:153], v[184:187], v[126:129]
	v_mfma_f32_16x16x32_bf16 v[122:125], v[154:157], v[180:183], v[122:125]
	v_mfma_f32_16x16x32_bf16 v[122:125], v[158:161], v[184:187], v[122:125]
	v_mfma_f32_16x16x32_bf16 v[114:117], v[146:149], v[216:219], v[114:117]
	v_mfma_f32_16x16x32_bf16 v[114:117], v[150:153], v[220:223], v[114:117]
	v_mfma_f32_16x16x32_bf16 v[106:109], v[154:157], v[216:219], v[106:109]
	v_mfma_f32_16x16x32_bf16 v[106:109], v[158:161], v[220:223], v[106:109]
	v_mfma_f32_16x16x32_bf16 v[98:101], v[146:149], v[224:227], v[98:101]
	v_mfma_f32_16x16x32_bf16 v[98:101], v[150:153], v[228:231], v[98:101]
	v_mfma_f32_16x16x32_bf16 v[90:93], v[154:157], v[224:227], v[90:93]
	v_mfma_f32_16x16x32_bf16 v[90:93], v[158:161], v[228:231], v[90:93]
	s_setprio 0
	s_setprio 1
	v_mfma_f32_16x16x32_bf16 v[118:121], v[166:169], v[2:5], v[118:121]
	v_mfma_f32_16x16x32_bf16 v[118:121], v[170:173], v[6:9], v[118:121]
	v_mfma_f32_16x16x32_bf16 v[2:5], v[174:177], v[2:5], v[110:113]
	v_mfma_f32_16x16x32_bf16 v[110:113], v[162:165], v[6:9], v[2:5]
	v_mfma_f32_16x16x32_bf16 v[2:5], v[166:169], v[180:183], v[102:105]
	v_mfma_f32_16x16x32_bf16 v[102:105], v[170:173], v[184:187], v[2:5]
	v_mfma_f32_16x16x32_bf16 v[2:5], v[174:177], v[180:183], v[94:97]
	v_mfma_f32_16x16x32_bf16 v[94:97], v[162:165], v[184:187], v[2:5]
	v_mfma_f32_16x16x32_bf16 v[2:5], v[166:169], v[216:219], v[86:89]
	v_mfma_f32_16x16x32_bf16 v[86:89], v[170:173], v[220:223], v[2:5]
	v_mfma_f32_16x16x32_bf16 v[2:5], v[174:177], v[216:219], v[82:85]
	v_mfma_f32_16x16x32_bf16 v[82:85], v[162:165], v[220:223], v[2:5]
	v_mfma_f32_16x16x32_bf16 v[2:5], v[166:169], v[224:227], v[78:81]
	v_mfma_f32_16x16x32_bf16 v[78:81], v[170:173], v[228:231], v[2:5]
	v_mfma_f32_16x16x32_bf16 v[2:5], v[174:177], v[224:227], v[74:77]
	v_mfma_f32_16x16x32_bf16 v[74:77], v[162:165], v[228:231], v[2:5]
	s_barrier
; #define PG8_SB(B) __builtin_amdgcn_rcpf(1.f + expneg(B))
; #define PG8_SB(B) __builtin_amdgcn_rcpf(1.f + expneg(B))
; #define PG8_STAGE(bufoff, gbase, voff) do { _Pragma("unroll") for (int _i = 0; _i < 2; ++_i) \
;         __builtin_amdgcn_global_load_lds((const unsigned*)((const char*)(gbase) + (size_t)_i * qstep + (voff)[0]), (PG8_LAS unsigned*)(lds + (bufoff) + ldsw + _i * 8192), 16, 0, 0); } while (0)
; #define PG8_LDA(dst, b, h) do { _Pragma("unroll") for (int m = 0; m < 4; ++m) _Pragma("unroll") for (int k = 0; k < 2; ++k) dst[m][k] = *(const PG8_LAS bf16x8*)(lds + PG8_SA(b, h) + aoff + m * 2048 + k * 1024); } while (0)
; #define PG8_MMA(ai, bj, At, Bt) do { __builtin_amdgcn_s_setprio(1); _Pragma("unroll") for (int m = 0; m < 4; ++m) _Pragma("unroll") for (int n = 0; n < 2; ++n) _Pragma("unroll") for (int k = 0; k < 2; ++k) \
;         acc[ai][bj][m][n] = __builtin_amdgcn_mfma_f32_16x16x32_bf16(Bt[n][k], At[m][k], acc[ai][bj][m][n], 0, 0, 0); __builtin_amdgcn_s_setprio(0); } while (0)
; #define PG8_WAIT_V89() do { if constexpr (SLIVER) PG8_WAIT_V(9); else PG8_WAIT_V(8); } while (0)
; #define PG8_LDS_S(b) do { if constexpr (SLIVER) { Sf[0] = *(const PG8_LAS bf16x8*)(lds + STAGE_BYTES + (b) * 2048 + soff0); Sf[1] = *(const PG8_LAS bf16x8*)(lds + STAGE_BYTES + (b) * 2048 + (soff0 ^ 64)); } } while (0)
; #define PG8_WAIT_L(n) asm volatile("s_waitcnt lgkmcnt(" #n ")" ::: "memory")
; #define PG8_BAR __builtin_amdgcn_s_barrier()
; #define PG8_SCHED __builtin_amdgcn_sched_barrier(0)
; template <class Epi, class Sched, bool ALIGN_EPI = false, bool SP2 = false, bool SLIVER = false>
; __device__ __forceinline__ void gemm_phase(PG8_LAS unsigned char* lds, const Gemm g, const Sched& S, const Epi& E) {
;     ...
;             PG8_LDA(At, 1, 1); PG8_LDS_S(1); PG8_STAGE(PG8_SB(1, 0), b3, voffB); PG8_STAGE(PG8_SB(1, 1), b3 + hstep, voffB); PG8_STAGE(PG8_SA(1, 0), a3, voffA);
;             PG8_WAIT_V89(); PG8_WAIT_L(0); PG8_BAR; PG8_MMA(1, 0, At, B0); PG8_MMA(1, 1, At, B1); PG8_MMA_S(); PG8_BAR; PG8_SCHED;
	s_setprio 0
	s_add_i32 s12, 0, 0x20800
	v_add_u32_e32 v178, s12, v213
	v_add_u32_e32 v184, s12, v214
	s_add_i32 s12, s68, s92
	v_lshl_add_u64 v[208:209], v[202:203], 0, s[26:27]
	s_mov_b32 m0, s12
	ds_read_b128 v[2:5], v215 offset:49152
	ds_read_b128 v[6:9], v215 offset:50176
	ds_read_b128 v[216:219], v215 offset:51200
	ds_read_b128 v[220:223], v215 offset:52224
	ds_read_b128 v[224:227], v215 offset:53248
	ds_read_b128 v[228:231], v215 offset:54272
	ds_read_b128 v[232:235], v215 offset:55296
	ds_read_b128 v[240:243], v215 offset:56320
	ds_read_b128 v[180:183], v178
	ds_read_b128 v[184:187], v184
	global_load_lds_dwordx4 v[208:209], off
	v_lshl_add_u64 v[208:209], v[202:203], 0, s[58:59]
	s_add_i32 m0, s12, 0x2000
	s_mov_b64 s[12:13], 0x90080
	global_load_lds_dwordx4 v[208:209], off
	v_lshl_add_u64 v[208:209], v[202:203], 0, s[12:13]
	s_add_i32 s12, s69, s92
	s_mov_b32 m0, s12
	s_mov_b64 s[68:69], 0xd8080
	global_load_lds_dwordx4 v[208:209], off
	v_lshl_add_u64 v[202:203], v[202:203], 0, s[68:69]
	s_add_i32 m0, s12, 0x2000
	s_nop 0
	global_load_lds_dwordx4 v[202:203], off
	v_lshl_add_u64 v[202:203], v[210:211], 0, s[26:27]
	s_mov_b32 m0, s51
	s_nop 0
	global_load_lds_dwordx4 v[202:203], off
	v_lshl_add_u64 v[202:203], v[210:211], 0, s[58:59]
	s_mov_b32 m0, s53
	s_nop 0
	global_load_lds_dwordx4 v[202:203], off
	s_waitcnt vmcnt(9)
	s_waitcnt lgkmcnt(0)
	s_setprio 1
	s_barrier
	v_mfma_f32_16x16x32_bf16 v[70:73], v[146:149], v[2:5], v[70:73]
	v_mfma_f32_16x16x32_bf16 v[70:73], v[150:153], v[6:9], v[70:73]
	v_mfma_f32_16x16x32_bf16 v[66:69], v[154:157], v[2:5], v[66:69]
	v_mfma_f32_16x16x32_bf16 v[66:69], v[158:161], v[6:9], v[66:69]
	v_mfma_f32_16x16x32_bf16 v[62:65], v[146:149], v[216:219], v[62:65]
	v_mfma_f32_16x16x32_bf16 v[62:65], v[150:153], v[220:223], v[62:65]
	v_mfma_f32_16x16x32_bf16 v[58:61], v[154:157], v[216:219], v[58:61]
	v_mfma_f32_16x16x32_bf16 v[58:61], v[158:161], v[220:223], v[58:61]
	v_mfma_f32_16x16x32_bf16 v[50:53], v[146:149], v[224:227], v[50:53]
	v_mfma_f32_16x16x32_bf16 v[50:53], v[150:153], v[228:231], v[50:53]
	v_mfma_f32_16x16x32_bf16 v[42:45], v[154:157], v[224:227], v[42:45]
	v_mfma_f32_16x16x32_bf16 v[42:45], v[158:161], v[228:231], v[42:45]
	v_mfma_f32_16x16x32_bf16 v[34:37], v[146:149], v[232:235], v[34:37]
	v_mfma_f32_16x16x32_bf16 v[34:37], v[150:153], v[240:243], v[34:37]
	v_mfma_f32_16x16x32_bf16 v[26:29], v[154:157], v[232:235], v[26:29]
	v_mfma_f32_16x16x32_bf16 v[26:29], v[158:161], v[240:243], v[26:29]
	s_setprio 0
	s_setprio 1
	v_mfma_f32_16x16x32_bf16 v[54:57], v[166:169], v[2:5], v[54:57]
	v_mfma_f32_16x16x32_bf16 v[54:57], v[170:173], v[6:9], v[54:57]
	v_mfma_f32_16x16x32_bf16 v[2:5], v[174:177], v[2:5], v[46:49]
	v_mfma_f32_16x16x32_bf16 v[46:49], v[162:165], v[6:9], v[2:5]
	v_mfma_f32_16x16x32_bf16 v[2:5], v[166:169], v[216:219], v[38:41]
	v_mfma_f32_16x16x32_bf16 v[38:41], v[170:173], v[220:223], v[2:5]
	v_mfma_f32_16x16x32_bf16 v[2:5], v[174:177], v[216:219], v[30:33]
	v_mfma_f32_16x16x32_bf16 v[30:33], v[162:165], v[220:223], v[2:5]
	v_mfma_f32_16x16x32_bf16 v[2:5], v[166:169], v[224:227], v[22:25]
	v_mfma_f32_16x16x32_bf16 v[22:25], v[170:173], v[228:231], v[2:5]
	v_mfma_f32_16x16x32_bf16 v[2:5], v[174:177], v[224:227], v[18:21]
	v_mfma_f32_16x16x32_bf16 v[18:21], v[162:165], v[228:231], v[2:5]
	v_mfma_f32_16x16x32_bf16 v[2:5], v[166:169], v[232:235], v[14:17]
	v_mfma_f32_16x16x32_bf16 v[14:17], v[170:173], v[240:243], v[2:5]
	v_mfma_f32_16x16x32_bf16 v[2:5], v[174:177], v[232:235], v[10:13]
	v_mfma_f32_16x16x32_bf16 v[10:13], v[162:165], v[240:243], v[2:5]
	s_setprio 0
	s_setprio 1
	s_and_b64 vcc, exec, s[90:91]
	s_cbranch_vccz .Lslv_c3
	v_mfma_f32_16x16x32_bf16 v[2:5], v[166:169], v[180:183], v[138:141]
	v_mfma_f32_16x16x32_bf16 v[6:9], v[170:173], v[184:187], v[2:5]
	v_mfma_f32_16x16x32_bf16 v[2:5], v[174:177], v[180:183], v[142:145]
	v_mfma_f32_16x16x32_bf16 v[2:5], v[162:165], v[184:187], v[2:5]
	s_branch .LBB0_933
